# phase-0 weight-conversion tiles: 4 source loads issued together with counted waits, gain slice prefetched (prologue de-serialisation), on top of v_prio
# speedup vs baseline: 1.0095x; 1.0069x over previous
.LBB0_83:
	s_add_i32 s26, s96, 63
	s_lshr_b32 s26, s26, 6
	v_cvt_f32_u32_e32 v0, s26
	s_sub_i32 s54, 0, s26
	s_abs_i32 s53, s95
	s_ashr_i32 s27, s95, 31
	v_rcp_iflag_f32_e32 v0, v0
	v_mov_b32_e32 v6, v220
	v_mov_b32_e32 v4, 0
	v_mul_f32_e32 v0, 0x4f7ffffe, v0
	v_cvt_u32_f32_e32 v0, v0
	v_ashrrev_i32_e32 v10, 4, v6
	v_mov_b32_e32 v5, 0
	v_readfirstlane_b32 s55, v0
	s_mul_i32 s54, s54, s55
	s_mul_hi_u32 s54, s55, s54
	s_add_i32 s55, s55, s54
	s_mul_hi_u32 s54, s53, s55
	s_mul_i32 s55, s54, s26
	s_sub_i32 s53, s53, s55
	s_add_i32 s56, s54, 1
	s_sub_i32 s55, s53, s26
	s_cmp_ge_u32 s53, s26
	s_cselect_b32 s54, s56, s54
	s_cselect_b32 s53, s55, s53
	s_add_i32 s55, s54, 1
	s_cmp_ge_u32 s53, s26
	s_cselect_b32 s53, s55, s54
	s_xor_b32 s53, s53, s27
	s_sub_i32 s27, s53, s27
	s_mul_i32 s26, s27, s26
	s_sub_i32 s26, s95, s26
	v_lshlrev_b32_e32 v0, 2, v6
	s_lshl_b32 s26, s26, 6
	v_and_b32_e32 v1, 60, v0
	v_or_b32_e32 v2, s26, v1
	v_ashrrev_i32_e32 v3, 31, v2
	s_lshl_b32 s94, s27, 6
	v_cmp_gt_i32_e32 vcc, s96, v2
	v_lshl_add_u64 v[8:9], v[2:3], 2, s[0:1]
	s_cmp_lg_u64 s[92:93], 0
	s_cbranch_scc0 .Lcv_nogain
	v_lshlrev_b32_e32 v102, 4, v6
	v_and_b32_e32 v102, 48, v102
	v_add_u32_e32 v102, s94, v102
	v_mov_b32_e32 v103, 0
	v_lshl_add_u64 v[102:103], v[102:103], 2, s[92:93]
	global_load_dwordx4 v[104:107], v[102:103], off
	global_load_dwordx4 v[108:111], v[102:103], off offset:16
	global_load_dwordx4 v[112:115], v[102:103], off offset:32
	global_load_dwordx4 v[116:119], v[102:103], off offset:48
.Lcv_nogain:
	v_mov_b32_e32 v2, 0
	v_mov_b32_e32 v3, 0
	v_mov_b32_e32 v4, 0
	v_mov_b32_e32 v5, 0
	v_mov_b32_e32 v82, 0
	v_mov_b32_e32 v83, 0
	v_mov_b32_e32 v84, 0
	v_mov_b32_e32 v85, 0
	v_mov_b32_e32 v86, 0
	v_mov_b32_e32 v87, 0
	v_mov_b32_e32 v88, 0
	v_mov_b32_e32 v89, 0
	v_mov_b32_e32 v90, 0
	v_mov_b32_e32 v91, 0
	v_mov_b32_e32 v92, 0
	v_mov_b32_e32 v93, 0
	s_and_saveexec_b64 s[0:1], vcc
	v_add3_u32 v94, v10, s94, 0
	v_mad_u64_u32 v[94:95], s[54:55], v94, s96, 0
	v_lshl_add_u64 v[94:95], v[94:95], 2, v[8:9]
	global_load_dwordx4 v[2:5], v[94:95], off nt
	v_add3_u32 v96, v10, s94, 16
	v_mad_u64_u32 v[96:97], s[54:55], v96, s96, 0
	v_lshl_add_u64 v[96:97], v[96:97], 2, v[8:9]
	global_load_dwordx4 v[82:85], v[96:97], off nt
	v_add3_u32 v98, v10, s94, 32
	v_mad_u64_u32 v[98:99], s[54:55], v98, s96, 0
	v_lshl_add_u64 v[98:99], v[98:99], 2, v[8:9]
	global_load_dwordx4 v[86:89], v[98:99], off nt
	v_add3_u32 v100, v10, s94, 48
	v_mad_u64_u32 v[100:101], s[54:55], v100, s96, 0
	v_lshl_add_u64 v[100:101], v[100:101], 2, v[8:9]
	global_load_dwordx4 v[90:93], v[100:101], off nt
	s_or_b64 exec, exec, s[0:1]
	s_movk_i32 s0, 0x104
	v_lshlrev_b32_e32 v1, 2, v1
	v_mul_lo_u32 v11, v10, s0
	v_add_u32_e32 v11, v1, v11
	v_ashrrev_i32_e32 v14, 2, v6
	s_waitcnt vmcnt(3)
	ds_write2_b32 v11, v2, v3 offset1:1
	ds_write2_b32 v11, v4, v5 offset0:2 offset1:3
	v_add_u32_e32 v94, 0x1040, v11
	v_add_u32_e32 v95, 0x1048, v11
	s_waitcnt vmcnt(2)
	ds_write2_b32 v94, v82, v83 offset1:1
	ds_write2_b32 v95, v84, v85 offset1:1
	v_add_u32_e32 v94, 0x2080, v11
	v_add_u32_e32 v95, 0x2088, v11
	s_waitcnt vmcnt(1)
	ds_write2_b32 v94, v86, v87 offset1:1
	ds_write2_b32 v95, v88, v89 offset1:1
	v_add_u32_e32 v94, 0x30c0, v11
	v_add_u32_e32 v95, 0x30c8, v11
	s_waitcnt vmcnt(0)
	ds_write2_b32 v94, v90, v91 offset1:1
	ds_write2_b32 v95, v92, v93 offset1:1
	v_add_u32_e32 v0, s26, v14
	v_cmp_gt_i32_e32 vcc, s96, v0
	s_waitcnt lgkmcnt(0)
	s_barrier
	s_and_saveexec_b64 s[96:97], vcc
	s_cbranch_execz .LBB0_21
	s_cmp_gt_i32 s52, 1
	s_mov_b64 s[0:1], -1
	s_cbranch_scc0 .LBB0_100
	v_cmp_lt_i32_e32 vcc, s3, v0
	v_mov_b32_e32 v20, v0
	s_and_saveexec_b64 s[0:1], vcc
	s_cbranch_execz .LBB0_99
	s_movk_i32 s26, 0xfff
	v_cmp_lt_u32_e32 vcc, s26, v0
	s_and_saveexec_b64 s[26:27], vcc
	s_xor_b64 s[26:27], exec, s[26:27]
	v_add_u32_e32 v20, 0xfffff800, v0
	s_andn2_saveexec_b64 s[26:27], s[26:27]
	v_add_u32_e32 v20, 0x80, v0
	s_or_b64 exec, exec, s[26:27]

.LBB0_104:
	v_lshlrev_b32_e32 v0, 4, v6
	v_and_b32_e32 v6, 48, v0
	v_mul_u32_u24_e32 v0, 0x41, v6
	v_lshlrev_b32_e32 v3, 2, v0
	v_lshl_add_u32 v2, v14, 2, v3
	ds_read2_b32 v[0:1], v2 offset1:65
	s_cmp_lg_u64 s[92:93], 0
	s_cselect_b64 s[26:27], -1, 0
	s_cmp_eq_u64 s[92:93], 0
	s_cbranch_scc1 .LBB0_106
	v_or_b32_e32 v4, s94, v6
	v_ashrrev_i32_e32 v5, 31, v4
	v_lshl_add_u64 v[4:5], v[4:5], 2, s[92:93]
	v_mov_b64_e32 v[4:5], v[104:105]
	s_waitcnt vmcnt(0) lgkmcnt(0)
	v_pk_mul_f32 v[0:1], v[0:1], v[4:5]
.LBB0_106:
	v_add_u32_e32 v5, 0x208, v3
	v_lshl_add_u32 v4, v14, 2, v5
	ds_read_b32 v2, v2 offset:520
	ds_read_b32 v3, v4 offset:260
	v_cndmask_b32_e64 v8, 0, 1, s[26:27]
	v_cmp_ne_u32_e64 s[0:1], 1, v8
	s_andn2_b64 vcc, exec, s[26:27]
	s_cbranch_vccnz .LBB0_108
	s_ashr_i32 s95, s94, 31
	v_lshl_add_u64 v[8:9], v[6:7], 0, s[94:95]
	v_lshl_add_u64 v[8:9], v[8:9], 2, s[92:93]
	v_mov_b64_e32 v[8:9], v[106:107]
	s_waitcnt vmcnt(0) lgkmcnt(0)
	v_pk_mul_f32 v[2:3], v[2:3], v[8:9]
.LBB0_108:
	v_add_u32_e32 v9, 0x208, v5
	v_lshl_add_u32 v8, v14, 2, v9
	ds_read_b32 v4, v4 offset:520
	ds_read_b32 v5, v8 offset:260
	s_and_b64 vcc, exec, s[0:1]
	s_cbranch_vccnz .LBB0_110
	s_ashr_i32 s95, s94, 31
	v_lshl_add_u64 v[10:11], v[6:7], 0, s[94:95]
	v_lshl_add_u64 v[10:11], v[10:11], 2, s[92:93]
	v_mov_b64_e32 v[10:11], v[108:109]
	s_waitcnt vmcnt(0) lgkmcnt(0)
	v_pk_mul_f32 v[4:5], v[4:5], v[10:11]
.LBB0_110:
	v_add_u32_e32 v11, 0x208, v9
	v_lshl_add_u32 v10, v14, 2, v11
	ds_read_b32 v8, v8 offset:520
	ds_read_b32 v9, v10 offset:260
	s_and_b64 vcc, exec, s[0:1]
	s_cbranch_vccnz .LBB0_112
	s_ashr_i32 s95, s94, 31
	v_lshl_add_u64 v[12:13], v[6:7], 0, s[94:95]
	v_lshl_add_u64 v[12:13], v[12:13], 2, s[92:93]
	v_mov_b64_e32 v[12:13], v[110:111]
	s_waitcnt vmcnt(0) lgkmcnt(0)
	v_pk_mul_f32 v[8:9], v[8:9], v[12:13]
.LBB0_112:
	v_add_u32_e32 v13, 0x208, v11
	v_lshl_add_u32 v12, v14, 2, v13
	ds_read_b32 v10, v10 offset:520
	ds_read_b32 v11, v12 offset:260
	s_and_b64 vcc, exec, s[0:1]
	s_cbranch_vccnz .LBB0_114
	s_ashr_i32 s95, s94, 31
	v_lshl_add_u64 v[16:17], v[6:7], 0, s[94:95]
	v_lshl_add_u64 v[16:17], v[16:17], 2, s[92:93]
	v_mov_b64_e32 v[16:17], v[112:113]
	s_waitcnt vmcnt(0) lgkmcnt(0)
	v_pk_mul_f32 v[10:11], v[10:11], v[16:17]
.LBB0_114:
	v_add_u32_e32 v16, 0x208, v13
	v_lshl_add_u32 v15, v14, 2, v16
	ds_read_b32 v12, v12 offset:520
	ds_read_b32 v13, v15 offset:260
	s_and_b64 vcc, exec, s[0:1]
	s_cbranch_vccnz .LBB0_116
	s_ashr_i32 s95, s94, 31
	v_lshl_add_u64 v[18:19], v[6:7], 0, s[94:95]
	v_lshl_add_u64 v[18:19], v[18:19], 2, s[92:93]
	v_mov_b64_e32 v[18:19], v[114:115]
	s_waitcnt vmcnt(0) lgkmcnt(0)
	v_pk_mul_f32 v[12:13], v[12:13], v[18:19]
.LBB0_116:
	v_add_u32_e32 v16, 0x208, v16
	v_lshl_add_u32 v16, v14, 2, v16
	ds_read_b32 v14, v15 offset:520
	ds_read_b32 v15, v16 offset:260
	s_and_b64 vcc, exec, s[0:1]
	s_cbranch_vccnz .LBB0_118
	s_ashr_i32 s95, s94, 31
	v_lshl_add_u64 v[18:19], v[6:7], 0, s[94:95]
	v_lshl_add_u64 v[18:19], v[18:19], 2, s[92:93]
	v_mov_b64_e32 v[18:19], v[116:117]
	s_waitcnt vmcnt(0) lgkmcnt(0)
	v_pk_mul_f32 v[14:15], v[14:15], v[18:19]
.LBB0_118:
	ds_read2_b32 v[18:19], v16 offset0:130 offset1:195
	s_and_b64 vcc, exec, s[26:27]
	s_cbranch_vccz .LBB0_120
	s_ashr_i32 s95, s94, 31
	v_lshl_add_u64 v[16:17], v[6:7], 0, s[94:95]
	v_lshl_add_u64 v[16:17], v[16:17], 2, s[92:93]
	v_mov_b64_e32 v[16:17], v[118:119]
	s_waitcnt vmcnt(0) lgkmcnt(0)
	v_pk_mul_f32 v[16:17], v[18:19], v[16:17]
	s_cbranch_execnz .LBB0_20
	s_branch .LBB0_19
